# GEMM: first main-loop iteration peeled with C=0 on the first MFMA into each accumulator; per-tile 128 v_mov accumulator clears removed
# speedup vs baseline: 1.0038x; 1.0038x over previous
; #define PG8_STAGE(bufoff, gbase, voff) do { _Pragma("unroll") for (int _i = 0; _i < 2; ++_i) \
;         __builtin_amdgcn_global_load_lds((const unsigned*)((const char*)(gbase) + (voff)[_i]), (LAS unsigned*)(lds + (bufoff) + ldsw + _i * 8192), 16, 0, 0); } while (0)
; #define PG8_LDA(dst, b, h) do { _Pragma("unroll") for (int m = 0; m < 4; ++m) _Pragma("unroll") for (int k = 0; k < 2; ++k) dst[m][k] = *(const LAS bf16x8*)(lds + PG8_SA(b, h) + aoff + m * 2048 + k * 1024); } while (0)
; #define PG8_LDB(dst, b, h) do { _Pragma("unroll") for (int n = 0; n < 2; ++n) _Pragma("unroll") for (int k = 0; k < 2; ++k) dst[n][k] = *(const LAS bf16x8*)(lds + PG8_SB(b, h) + boff + n * 2048 + k * 1024); } while (0)
; #define PG8_MMA(ai, bj, At, Bt) do { __builtin_amdgcn_s_setprio(1); _Pragma("unroll") for (int m = 0; m < 4; ++m) _Pragma("unroll") for (int n = 0; n < 2; ++n) _Pragma("unroll") for (int k = 0; k < 2; ++k) \
;         acc[ai][bj][m][n] = __builtin_amdgcn_mfma_f32_16x16x32_bf16(Bt[n][k], At[m][k], acc[ai][bj][m][n], 0, 0, 0); __builtin_amdgcn_s_setprio(0); } while (0)
; __device__ __forceinline__ void gemm_phase(LAS unsigned char* lds, const GemmD g, const Sched& S, const Epi& E) {
;     ...
;     f32x4 acc[2][2][4][2];
; #pragma unroll
;     for (int a = 0; a < 2; ++a)
; #pragma unroll
;         for (int b = 0; b < 2; ++b)
; #pragma unroll
;             for (int m = 0; m < 4; ++m)
; #pragma unroll
;                 for (int n = 0; n < 2; ++n) acc[a][b][m][n] = (f32x4){0.f, 0.f, 0.f, 0.f};
;     ...
;         for (int t = 0; t < nt; t += 2) {
;             const bool last = (t == nt - 2);
;             const char* a1 = cA + (size_t)(t + 1) * kstep;
;             const char* a2 = last ? nA : cA + (size_t)(t + 2) * kstep; const char* b2 = last ? nB : cB + (size_t)(t + 2) * kstep;
;             const char* a3 = a2 + kstep; const char* b3 = b2 + kstep;
;             PG8_LDB(B0, 0, 0); PG8_LDB(B1, 0, 1); PG8_SCHED; PG8_LDA(At, 0, 0); PG8_STAGE(PG8_SA(1, 1), a1 + hstepA, voffA);
;             PG8_WAIT_V(8); PG8_WAIT_L(0); PG8_BAR; PG8_MMA(0, 0, At, B0); PG8_MMA(0, 1, At, B1); PG8_BAR; PG8_SCHED;
;             PG8_LDA(At, 0, 1); PG8_STAGE(PG8_SB(0, 0), b2, voffB); PG8_STAGE(PG8_SB(0, 1), b2 + hstepB, voffB); PG8_STAGE(PG8_SA(0, 0), a2, voffA);
;             PG8_WAIT_V(8); PG8_WAIT_L(0); PG8_BAR; PG8_MMA(1, 0, At, B0); PG8_MMA(1, 1, At, B1); PG8_BAR; PG8_SCHED;
.LBB0_214:
	s_add_u32 s8, s8, 0x80
	s_addc_u32 s9, s9, 0
	s_add_u32 s34, s26, 0x100
	s_addc_u32 s35, s27, 0
	s_mov_b32 s26, 0
	v_readlane_b32 s22, v250, 17
	s_cmp_lg_u32 s22, 0
	s_cbranch_scc0 .Lprio_done
	s_setprio 1
.Lprio_done:
	v_add_u32_e32 v240, 0x10000, v160
	v_add_u32_e32 v241, 0x14000, v160
	v_add_u32_e32 v242, 0x18000, v160
	v_add_u32_e32 v243, 0x1c000, v160
	s_add_i32 s92, s26, 2
	s_add_u32 s93, s8, 0x80
	s_addc_u32 s27, s9, 0
	s_add_i32 s22, 0, 0x10000
	s_cmp_eq_u32 s11, s26
	s_cselect_b32 s27, s1, s27
	s_cselect_b32 s26, s0, s93
	s_cselect_b32 vcc_hi, s17, s35
	s_cselect_b32 vcc_lo, s16, s34
	s_add_i32 s23, 0, 0x14000
	ds_read_b128 v[130:133], v240
	ds_read_b128 v[146:149], v240 offset:1024
	ds_read_b128 v[150:153], v240 offset:2048
	ds_read_b128 v[154:157], v240 offset:3072
	ds_read_b128 v[162:165], v241
	ds_read_b128 v[166:169], v241 offset:1024
	ds_read_b128 v[170:173], v241 offset:2048
	ds_read_b128 v[174:177], v241 offset:3072
	s_add_i32 m0, s31, 0xc000
	ds_read_b128 v[182:185], v161
	ds_read_b128 v[186:189], v161 offset:1024
	ds_read_b128 v[190:193], v161 offset:2048
	ds_read_b128 v[216:219], v161 offset:3072
	ds_read_b128 v[220:223], v161 offset:4096
	ds_read_b128 v[224:227], v161 offset:5120
	ds_read_b128 v[228:231], v161 offset:6144
	ds_read_b128 v[236:239], v161 offset:7168
	global_load_lds_dwordx4 v142, s[8:9]
	s_add_i32 m0, s31, 0xe000
	s_nop 0
	global_load_lds_dwordx4 v144, s[8:9]
	s_waitcnt vmcnt(8)
	s_waitcnt lgkmcnt(0)
	s_barrier
	s_waitcnt lgkmcnt(0)
	v_mfma_f32_16x16x32_bf16 v[126:129], v[130:133], v[182:185], 0
	v_mfma_f32_16x16x32_bf16 v[122:125], v[150:153], v[182:185], 0
	v_mfma_f32_16x16x32_bf16 v[110:113], v[130:133], v[190:193], 0
	v_mfma_f32_16x16x32_bf16 v[106:109], v[150:153], v[190:193], 0
	v_mfma_f32_16x16x32_bf16 v[94:97], v[130:133], v[220:223], 0
	v_mfma_f32_16x16x32_bf16 v[90:93], v[150:153], v[220:223], 0
	v_mfma_f32_16x16x32_bf16 v[78:81], v[130:133], v[228:231], 0
	v_mfma_f32_16x16x32_bf16 v[74:77], v[150:153], v[228:231], 0
	v_mfma_f32_16x16x32_bf16 v[126:129], v[146:149], v[186:189], v[126:129]
	v_mfma_f32_16x16x32_bf16 v[122:125], v[154:157], v[186:189], v[122:125]
	v_mfma_f32_16x16x32_bf16 v[110:113], v[146:149], v[216:219], v[110:113]
	v_mfma_f32_16x16x32_bf16 v[106:109], v[154:157], v[216:219], v[106:109]
	v_mfma_f32_16x16x32_bf16 v[94:97], v[146:149], v[224:227], v[94:97]
	v_mfma_f32_16x16x32_bf16 v[90:93], v[154:157], v[224:227], v[90:93]
	v_mfma_f32_16x16x32_bf16 v[78:81], v[146:149], v[236:239], v[78:81]
	v_mfma_f32_16x16x32_bf16 v[74:77], v[154:157], v[236:239], v[74:77]
	v_mfma_f32_16x16x32_bf16 v[118:121], v[162:165], v[182:185], 0
	v_mfma_f32_16x16x32_bf16 v[114:117], v[170:173], v[182:185], 0
	v_mfma_f32_16x16x32_bf16 v[102:105], v[162:165], v[190:193], 0
	v_mfma_f32_16x16x32_bf16 v[98:101], v[170:173], v[190:193], 0
	v_mfma_f32_16x16x32_bf16 v[86:89], v[162:165], v[220:223], 0
	v_mfma_f32_16x16x32_bf16 v[82:85], v[170:173], v[220:223], 0
	v_mfma_f32_16x16x32_bf16 v[70:73], v[162:165], v[228:231], 0
	v_mfma_f32_16x16x32_bf16 v[66:69], v[170:173], v[228:231], 0
	v_mfma_f32_16x16x32_bf16 v[118:121], v[166:169], v[186:189], v[118:121]
	v_mfma_f32_16x16x32_bf16 v[114:117], v[174:177], v[186:189], v[114:117]
	v_mfma_f32_16x16x32_bf16 v[102:105], v[166:169], v[216:219], v[102:105]
	v_mfma_f32_16x16x32_bf16 v[98:101], v[174:177], v[216:219], v[98:101]
	v_mfma_f32_16x16x32_bf16 v[86:89], v[166:169], v[224:227], v[86:89]
	v_mfma_f32_16x16x32_bf16 v[82:85], v[174:177], v[224:227], v[82:85]
	v_mfma_f32_16x16x32_bf16 v[70:73], v[166:169], v[236:239], v[70:73]
	v_mfma_f32_16x16x32_bf16 v[66:69], v[174:177], v[236:239], v[66:69]
	s_barrier
	s_add_i32 s22, s22, s30
	s_mov_b32 m0, s22
	ds_read_b128 v[182:185], v161 offset:16384
	ds_read_b128 v[186:189], v161 offset:17408
	ds_read_b128 v[190:193], v161 offset:18432
	ds_read_b128 v[216:219], v161 offset:19456
	ds_read_b128 v[220:223], v161 offset:20480
	ds_read_b128 v[224:227], v161 offset:21504
	ds_read_b128 v[228:231], v161 offset:22528
	ds_read_b128 v[236:239], v161 offset:23552
	global_load_lds_dwordx4 v136, vcc
	s_add_i32 m0, s22, 0x2000
	s_add_i32 s22, s23, s30
	global_load_lds_dwordx4 v140, vcc
	s_mov_b32 m0, s22
	s_nop 0
	global_load_lds_dwordx4 v253, vcc
	s_add_i32 m0, s22, 0x2000
	s_nop 0
	global_load_lds_dwordx4 v254, vcc
	s_mov_b32 m0, s31
	s_nop 0
	global_load_lds_dwordx4 v134, s[26:27]
	s_mov_b32 m0, s14
	s_nop 0
	global_load_lds_dwordx4 v138, s[26:27]
	s_waitcnt vmcnt(8)
	s_waitcnt lgkmcnt(0)
	s_barrier
	s_waitcnt lgkmcnt(0)
	v_mfma_f32_16x16x32_bf16 v[62:65], v[130:133], v[182:185], 0
	v_mfma_f32_16x16x32_bf16 v[58:61], v[150:153], v[182:185], 0
	v_mfma_f32_16x16x32_bf16 v[46:49], v[130:133], v[190:193], 0
	v_mfma_f32_16x16x32_bf16 v[42:45], v[150:153], v[190:193], 0
	v_mfma_f32_16x16x32_bf16 v[30:33], v[130:133], v[220:223], 0
	v_mfma_f32_16x16x32_bf16 v[26:29], v[150:153], v[220:223], 0
	v_mfma_f32_16x16x32_bf16 v[14:17], v[130:133], v[228:231], 0
	v_mfma_f32_16x16x32_bf16 v[10:13], v[150:153], v[228:231], 0
	v_mfma_f32_16x16x32_bf16 v[62:65], v[146:149], v[186:189], v[62:65]
	v_mfma_f32_16x16x32_bf16 v[58:61], v[154:157], v[186:189], v[58:61]
	v_mfma_f32_16x16x32_bf16 v[46:49], v[146:149], v[216:219], v[46:49]
	v_mfma_f32_16x16x32_bf16 v[42:45], v[154:157], v[216:219], v[42:45]
	v_mfma_f32_16x16x32_bf16 v[30:33], v[146:149], v[224:227], v[30:33]
	v_mfma_f32_16x16x32_bf16 v[26:29], v[154:157], v[224:227], v[26:29]
	v_mfma_f32_16x16x32_bf16 v[14:17], v[146:149], v[236:239], v[14:17]
	v_mfma_f32_16x16x32_bf16 v[10:13], v[154:157], v[236:239], v[10:13]
	v_mfma_f32_16x16x32_bf16 v[54:57], v[162:165], v[182:185], 0
	v_mfma_f32_16x16x32_bf16 v[50:53], v[170:173], v[182:185], 0
	v_mfma_f32_16x16x32_bf16 v[38:41], v[162:165], v[190:193], 0
	v_mfma_f32_16x16x32_bf16 v[34:37], v[170:173], v[190:193], 0
	v_mfma_f32_16x16x32_bf16 v[22:25], v[162:165], v[220:223], 0
	v_mfma_f32_16x16x32_bf16 v[18:21], v[170:173], v[220:223], 0
	v_mfma_f32_16x16x32_bf16 v[6:9], v[162:165], v[228:231], 0
	v_mfma_f32_16x16x32_bf16 v[2:5], v[170:173], v[228:231], 0
	v_mfma_f32_16x16x32_bf16 v[54:57], v[166:169], v[186:189], v[54:57]
	v_mfma_f32_16x16x32_bf16 v[50:53], v[174:177], v[186:189], v[50:53]
	v_mfma_f32_16x16x32_bf16 v[38:41], v[166:169], v[216:219], v[38:41]
	v_mfma_f32_16x16x32_bf16 v[34:37], v[174:177], v[216:219], v[34:37]
	v_mfma_f32_16x16x32_bf16 v[22:25], v[166:169], v[224:227], v[22:25]
	v_mfma_f32_16x16x32_bf16 v[18:21], v[174:177], v[224:227], v[18:21]
	v_mfma_f32_16x16x32_bf16 v[6:9], v[166:169], v[236:239], v[6:9]
	v_mfma_f32_16x16x32_bf16 v[2:5], v[174:177], v[236:239], v[2:5]
	s_barrier
; #define PG8_STAGE(bufoff, gbase, voff) do { _Pragma("unroll") for (int _i = 0; _i < 2; ++_i) \
;         __builtin_amdgcn_global_load_lds((const unsigned*)((const char*)(gbase) + (voff)[_i]), (LAS unsigned*)(lds + (bufoff) + ldsw + _i * 8192), 16, 0, 0); } while (0)
; #define PG8_LDA(dst, b, h) do { _Pragma("unroll") for (int m = 0; m < 4; ++m) _Pragma("unroll") for (int k = 0; k < 2; ++k) dst[m][k] = *(const LAS bf16x8*)(lds + PG8_SA(b, h) + aoff + m * 2048 + k * 1024); } while (0)
; #define PG8_LDB(dst, b, h) do { _Pragma("unroll") for (int n = 0; n < 2; ++n) _Pragma("unroll") for (int k = 0; k < 2; ++k) dst[n][k] = *(const LAS bf16x8*)(lds + PG8_SB(b, h) + boff + n * 2048 + k * 1024); } while (0)
; #define PG8_MMA(ai, bj, At, Bt) do { __builtin_amdgcn_s_setprio(1); _Pragma("unroll") for (int m = 0; m < 4; ++m) _Pragma("unroll") for (int n = 0; n < 2; ++n) _Pragma("unroll") for (int k = 0; k < 2; ++k) \
;         acc[ai][bj][m][n] = __builtin_amdgcn_mfma_f32_16x16x32_bf16(Bt[n][k], At[m][k], acc[ai][bj][m][n], 0, 0, 0); __builtin_amdgcn_s_setprio(0); } while (0)
; #define PG8_WAIT_V(n) asm volatile("s_waitcnt vmcnt(" #n ")" ::: "memory")
; #define PG8_WAIT_L(n) asm volatile("s_waitcnt lgkmcnt(" #n ")" ::: "memory")
; #define PG8_BAR __builtin_amdgcn_s_barrier()
; #define PG8_SCHED __builtin_amdgcn_sched_barrier(0)
; __device__ __forceinline__ void gemm_phase(LAS unsigned char* lds, const GemmD g, const Sched& S, const Epi& E) {
;     ...
;             PG8_LDB(B0, 1, 0); PG8_LDB(B1, 1, 1); PG8_SCHED; PG8_LDA(At, 1, 0); PG8_STAGE(PG8_SA(0, 1), a2 + hstepA, voffA);
;             PG8_WAIT_V(8); PG8_WAIT_L(0); PG8_BAR; PG8_MMA(0, 0, At, B0); PG8_MMA(0, 1, At, B1); PG8_BAR; PG8_SCHED;
;             PG8_LDA(At, 1, 1); PG8_STAGE(PG8_SB(1, 0), b3, voffB); PG8_STAGE(PG8_SB(1, 1), b3 + hstepB, voffB); PG8_STAGE(PG8_SA(1, 0), a3, voffA);
;             PG8_WAIT_V(8); PG8_WAIT_L(0); PG8_BAR; PG8_MMA(1, 0, At, B0); PG8_MMA(1, 1, At, B1); PG8_BAR; PG8_SCHED;
;         }
	s_add_i32 s22, 0, 0x18000
	s_add_i32 s23, 0, 0x1c000
	ds_read_b128 v[130:133], v242
	ds_read_b128 v[146:149], v242 offset:1024
	ds_read_b128 v[150:153], v242 offset:2048
	ds_read_b128 v[154:157], v242 offset:3072
	ds_read_b128 v[162:165], v243
	ds_read_b128 v[166:169], v243 offset:1024
	ds_read_b128 v[170:173], v243 offset:2048
	ds_read_b128 v[174:177], v243 offset:3072
	s_mov_b32 m0, s15
	ds_read_b128 v[182:185], v161 offset:32768
	ds_read_b128 v[186:189], v161 offset:33792
	ds_read_b128 v[190:193], v161 offset:34816
	ds_read_b128 v[216:219], v161 offset:35840
	ds_read_b128 v[220:223], v161 offset:36864
	ds_read_b128 v[224:227], v161 offset:37888
	ds_read_b128 v[228:231], v161 offset:38912
	ds_read_b128 v[236:239], v161 offset:39936
	global_load_lds_dwordx4 v142, s[26:27]
	s_mov_b32 m0, s10
	s_nop 0
	global_load_lds_dwordx4 v144, s[26:27]
	s_waitcnt vmcnt(8)
	s_waitcnt lgkmcnt(0)
	s_barrier
	s_waitcnt lgkmcnt(0)
	v_mfma_f32_16x16x32_bf16 v[126:129], v[130:133], v[182:185], v[126:129]
	v_mfma_f32_16x16x32_bf16 v[122:125], v[150:153], v[182:185], v[122:125]
	v_mfma_f32_16x16x32_bf16 v[110:113], v[130:133], v[190:193], v[110:113]
	v_mfma_f32_16x16x32_bf16 v[106:109], v[150:153], v[190:193], v[106:109]
	v_mfma_f32_16x16x32_bf16 v[94:97], v[130:133], v[220:223], v[94:97]
	v_mfma_f32_16x16x32_bf16 v[90:93], v[150:153], v[220:223], v[90:93]
	v_mfma_f32_16x16x32_bf16 v[78:81], v[130:133], v[228:231], v[78:81]
	v_mfma_f32_16x16x32_bf16 v[74:77], v[150:153], v[228:231], v[74:77]
	v_mfma_f32_16x16x32_bf16 v[126:129], v[146:149], v[186:189], v[126:129]
	v_mfma_f32_16x16x32_bf16 v[122:125], v[154:157], v[186:189], v[122:125]
	v_mfma_f32_16x16x32_bf16 v[110:113], v[146:149], v[216:219], v[110:113]
	v_mfma_f32_16x16x32_bf16 v[106:109], v[154:157], v[216:219], v[106:109]
	v_mfma_f32_16x16x32_bf16 v[94:97], v[146:149], v[224:227], v[94:97]
	v_mfma_f32_16x16x32_bf16 v[90:93], v[154:157], v[224:227], v[90:93]
	v_mfma_f32_16x16x32_bf16 v[78:81], v[146:149], v[236:239], v[78:81]
	v_mfma_f32_16x16x32_bf16 v[74:77], v[154:157], v[236:239], v[74:77]
	v_mfma_f32_16x16x32_bf16 v[118:121], v[162:165], v[182:185], v[118:121]
	v_mfma_f32_16x16x32_bf16 v[114:117], v[170:173], v[182:185], v[114:117]
	v_mfma_f32_16x16x32_bf16 v[102:105], v[162:165], v[190:193], v[102:105]
	v_mfma_f32_16x16x32_bf16 v[98:101], v[170:173], v[190:193], v[98:101]
	v_mfma_f32_16x16x32_bf16 v[86:89], v[162:165], v[220:223], v[86:89]
	v_mfma_f32_16x16x32_bf16 v[82:85], v[170:173], v[220:223], v[82:85]
	v_mfma_f32_16x16x32_bf16 v[70:73], v[162:165], v[228:231], v[70:73]
	v_mfma_f32_16x16x32_bf16 v[66:69], v[170:173], v[228:231], v[66:69]
	v_mfma_f32_16x16x32_bf16 v[118:121], v[166:169], v[186:189], v[118:121]
	v_mfma_f32_16x16x32_bf16 v[114:117], v[174:177], v[186:189], v[114:117]
	v_mfma_f32_16x16x32_bf16 v[102:105], v[166:169], v[216:219], v[102:105]
	v_mfma_f32_16x16x32_bf16 v[98:101], v[174:177], v[216:219], v[98:101]
	v_mfma_f32_16x16x32_bf16 v[86:89], v[166:169], v[224:227], v[86:89]
	v_mfma_f32_16x16x32_bf16 v[82:85], v[174:177], v[224:227], v[82:85]
	v_mfma_f32_16x16x32_bf16 v[70:73], v[166:169], v[236:239], v[70:73]
	v_mfma_f32_16x16x32_bf16 v[66:69], v[174:177], v[236:239], v[66:69]
	s_barrier
	s_add_i32 s22, s22, s30
	s_add_u32 vcc_lo, vcc_lo, s84
	s_addc_u32 vcc_hi, vcc_hi, s85
	s_add_u32 s26, s26, s84
	s_addc_u32 s27, s27, s85
	s_mov_b32 m0, s22
	ds_read_b128 v[182:185], v161 offset:49152
	ds_read_b128 v[186:189], v161 offset:50176
	ds_read_b128 v[190:193], v161 offset:51200
	ds_read_b128 v[216:219], v161 offset:52224
	ds_read_b128 v[220:223], v161 offset:53248
	ds_read_b128 v[224:227], v161 offset:54272
	ds_read_b128 v[228:231], v161 offset:55296
	ds_read_b128 v[236:239], v161 offset:56320
	global_load_lds_dwordx4 v136, vcc
	s_add_i32 m0, s22, 0x2000
	s_add_i32 s22, s23, s30
	global_load_lds_dwordx4 v140, vcc
	s_mov_b32 m0, s22
	s_nop 0
	global_load_lds_dwordx4 v253, vcc
	s_add_i32 m0, s22, 0x2000
	s_nop 0
	global_load_lds_dwordx4 v254, vcc
	s_mov_b32 m0, s18
	s_nop 0
	global_load_lds_dwordx4 v134, s[26:27]
	s_mov_b32 m0, s19
	s_nop 0
	global_load_lds_dwordx4 v138, s[26:27]
	s_waitcnt vmcnt(8)
	s_waitcnt lgkmcnt(0)
	s_barrier
	s_waitcnt lgkmcnt(0)
	v_mfma_f32_16x16x32_bf16 v[62:65], v[130:133], v[182:185], v[62:65]
	v_mfma_f32_16x16x32_bf16 v[58:61], v[150:153], v[182:185], v[58:61]
	v_mfma_f32_16x16x32_bf16 v[46:49], v[130:133], v[190:193], v[46:49]
	v_mfma_f32_16x16x32_bf16 v[42:45], v[150:153], v[190:193], v[42:45]
	v_mfma_f32_16x16x32_bf16 v[30:33], v[130:133], v[220:223], v[30:33]
	v_mfma_f32_16x16x32_bf16 v[26:29], v[150:153], v[220:223], v[26:29]
	v_mfma_f32_16x16x32_bf16 v[14:17], v[130:133], v[228:231], v[14:17]
	v_mfma_f32_16x16x32_bf16 v[10:13], v[150:153], v[228:231], v[10:13]
	v_mfma_f32_16x16x32_bf16 v[62:65], v[146:149], v[186:189], v[62:65]
	v_mfma_f32_16x16x32_bf16 v[58:61], v[154:157], v[186:189], v[58:61]
	v_mfma_f32_16x16x32_bf16 v[46:49], v[146:149], v[216:219], v[46:49]
	v_mfma_f32_16x16x32_bf16 v[42:45], v[154:157], v[216:219], v[42:45]
	v_mfma_f32_16x16x32_bf16 v[30:33], v[146:149], v[224:227], v[30:33]
	v_mfma_f32_16x16x32_bf16 v[26:29], v[154:157], v[224:227], v[26:29]
	v_mfma_f32_16x16x32_bf16 v[14:17], v[146:149], v[236:239], v[14:17]
	v_mfma_f32_16x16x32_bf16 v[10:13], v[154:157], v[236:239], v[10:13]
	v_mfma_f32_16x16x32_bf16 v[54:57], v[162:165], v[182:185], v[54:57]
	v_mfma_f32_16x16x32_bf16 v[50:53], v[170:173], v[182:185], v[50:53]
	v_mfma_f32_16x16x32_bf16 v[38:41], v[162:165], v[190:193], v[38:41]
	v_mfma_f32_16x16x32_bf16 v[34:37], v[170:173], v[190:193], v[34:37]
	v_mfma_f32_16x16x32_bf16 v[22:25], v[162:165], v[220:223], v[22:25]
	v_mfma_f32_16x16x32_bf16 v[18:21], v[170:173], v[220:223], v[18:21]
	v_mfma_f32_16x16x32_bf16 v[6:9], v[162:165], v[228:231], v[6:9]
	v_mfma_f32_16x16x32_bf16 v[2:5], v[170:173], v[228:231], v[2:5]
	v_mfma_f32_16x16x32_bf16 v[54:57], v[166:169], v[186:189], v[54:57]
	v_mfma_f32_16x16x32_bf16 v[50:53], v[174:177], v[186:189], v[50:53]
	v_mfma_f32_16x16x32_bf16 v[38:41], v[166:169], v[216:219], v[38:41]
	v_mfma_f32_16x16x32_bf16 v[34:37], v[174:177], v[216:219], v[34:37]
	v_mfma_f32_16x16x32_bf16 v[22:25], v[166:169], v[224:227], v[22:25]
	v_mfma_f32_16x16x32_bf16 v[18:21], v[174:177], v[224:227], v[18:21]
	v_mfma_f32_16x16x32_bf16 v[6:9], v[166:169], v[236:239], v[6:9]
	v_mfma_f32_16x16x32_bf16 v[2:5], v[174:177], v[236:239], v[2:5]
	s_barrier
	s_add_u32 s8, s8, 0x100
	s_addc_u32 s9, s9, 0
	s_add_u32 s34, s34, 0x100
	s_addc_u32 s35, s35, 0
	s_cmp_ge_u32 s92, s12
	s_mov_b32 s26, s92
	s_cbranch_scc0 .LBB0_215
	s_branch .Lgemm_after

; #define PG8_BAR __builtin_amdgcn_s_barrier()
; __device__ __forceinline__ void gemm_phase(LAS unsigned char* lds, const GemmD g, const Sched& S, const Epi& E) {
;     ...
;         }
;         if (wr == 0) PG8_BAR;
;         epi_run(E, acc, cur, wr, wc, fr, fq);
.Lgemm_after:
	s_setprio 0
	v_readlane_b32 s8, v250, 24
	v_readlane_b32 s9, v250, 25
	s_and_b64 vcc, exec, s[8:9]
	s_cbranch_vccz .LBB0_219
	s_barrier
	s_cmp_lt_i32 s96, 4
	s_mov_b64 s[8:9], -1
	s_cbranch_scc0 .LBB0_220

; template <bool COOP>
; __global__ void __launch_bounds__(512, 2) fwd_kernel(Params p) {
;     ...
;     }
; }
.LBB0_641:
	s_nop 0
	s_nop 0
	s_nop 0
	s_nop 0
	s_nop 0
	s_nop 0
	s_nop 0
	s_nop 0
	s_nop 0
	s_nop 0
	s_nop 0
	s_nop 0
	s_nop 0
	s_nop 0
	s_nop 0
	s_nop 0
	s_nop 0
	s_nop 0
	s_nop 0
	s_nop 0
	s_nop 0
	s_nop 0
	s_nop 0
	s_nop 0
	s_nop 0
	s_nop 0
	s_nop 0
	s_nop 0
	s_nop 0
	s_nop 0
	s_nop 0
	s_nop 0
	s_nop 0
	s_nop 0
	s_nop 0
	s_nop 0
	s_nop 0
	s_nop 0
	s_nop 0
	s_nop 0
	s_nop 0
	s_nop 0
	s_nop 0
	s_nop 0
	s_nop 0
	s_nop 0
	s_nop 0
	s_nop 0
	s_nop 0
	s_nop 0
	s_nop 0
	s_nop 0
	s_nop 0
	s_nop 0
	s_nop 0
	s_nop 0
	s_nop 0
	s_nop 0
	s_nop 0
	s_nop 0
	s_nop 0
	s_nop 0
	s_nop 0
	s_nop 0
	s_nop 0
	s_nop 0
	s_nop 0
	s_nop 0
	s_nop 0
	s_nop 0
	s_nop 0
	s_nop 0
	s_nop 0
	s_nop 0
	s_nop 0
	s_nop 0
	s_nop 0
	s_nop 0
	s_nop 0
	s_nop 0
	s_nop 0
	s_nop 0
	s_nop 0
	s_nop 0
	s_nop 0
	s_nop 0
	s_nop 0
	s_nop 0
	s_nop 0
	s_nop 0
	s_nop 0
	s_nop 0
	s_nop 0
	s_nop 0
	s_nop 0
	s_nop 0
	s_nop 0
	s_nop 0
	s_nop 0
	s_nop 0
	s_nop 0
	s_nop 0
	s_nop 0
	s_nop 0
	s_nop 0
	s_nop 0
	s_nop 0
	s_nop 0
	s_nop 0
	s_nop 0
	s_nop 0
	s_nop 0
	s_nop 0
	s_nop 0
	s_nop 0
	s_nop 0
	s_nop 0
	s_nop 0
	s_nop 0
	s_nop 0
	s_nop 0
	s_nop 0
	s_nop 0
	s_nop 0
	s_nop 0
	s_nop 0
	s_nop 0
	s_nop 0
	s_nop 0
	s_nop 0
	s_nop 0
	s_nop 0
	s_nop 0
	s_nop 0
	s_nop 0
	s_nop 0
	s_nop 0
	s_nop 0
	s_nop 0
	s_nop 0
	s_nop 0
	s_nop 0
	s_nop 0
	s_nop 0
	s_nop 0
	s_nop 0
	s_nop 0
	s_nop 0
	s_nop 0
	s_nop 0
	s_nop 0
	s_nop 0
	s_nop 0
	s_nop 0
	s_nop 0
	s_nop 0
	s_nop 0
	s_nop 0
	s_nop 0
	s_nop 0
	s_nop 0
	s_nop 0
	s_nop 0
	s_nop 0
	s_nop 0
	s_nop 0
	s_nop 0
	s_nop 0
	s_nop 0
	s_nop 0
	s_nop 0
	s_nop 0
	s_nop 0
	s_nop 0
	s_nop 0
	s_nop 0
	s_nop 0
	s_nop 0
	s_nop 0
	s_nop 0
	s_nop 0
	s_nop 0
	s_nop 0
	s_nop 0
	s_nop 0
	s_nop 0
	s_nop 0
	s_nop 0
	s_nop 0
	s_nop 0
	s_nop 0
	s_nop 0
	s_nop 0
	s_nop 0
	s_nop 0
	s_nop 0
	s_nop 0
	s_nop 0
	s_nop 0
	s_nop 0
	s_nop 0
	s_nop 0
	s_nop 0
	s_nop 0
	s_nop 0
	s_nop 0
	s_nop 0
	s_nop 0
	s_nop 0
	s_nop 0
	s_nop 0
	s_nop 0
	s_nop 0
	s_nop 0
	s_nop 0
	s_nop 0
	s_nop 0
	s_nop 0
	s_nop 0
	s_nop 0
	s_nop 0
	s_nop 0
	s_nop 0
	s_nop 0
	s_nop 0
	s_nop 0
	s_nop 0
	s_nop 0
	s_nop 0
	s_nop 0
	s_nop 0
	s_nop 0
	s_nop 0
	s_endpgm
